# v27 + P4 epilogue: the 8 rstd LDS reads hoisted to the top with counted lgkmcnt
# baseline (speedup 1.0000x reference)
.LBB0_629:
	ds_read_b32 v200, v151
	ds_read_b32 v202, v153
	ds_read_b32 v204, v155
	ds_read_b32 v206, v157
	ds_read_b32 v208, v159
	ds_read_b32 v210, v161
	ds_read_b32 v212, v163
	ds_read_b32 v214, v165
	s_lshl_b32 s31, s42, 8
	v_add_u32_e32 v172, s31, v149
	v_lshl_or_b32 v146, s40, 8, v166
	v_ashrrev_i32_e32 v173, 31, v172
	s_waitcnt lgkmcnt(7)
	v_pk_mul_f32 v[124:125], v[124:125], v[200:201] op_sel_hi:[1,0]
	v_pk_mul_f32 v[122:123], v[122:123], v[200:201] op_sel_hi:[1,0]
	v_pk_mul_f32 v[128:129], v[128:129], v[200:201] op_sel_hi:[1,0]
	v_pk_mul_f32 v[126:127], v[126:127], v[200:201] op_sel_hi:[1,0]
	v_max_f32_e32 v122, 0, v122
	v_max_f32_e32 v123, 0, v123
	v_max_f32_e32 v124, 0, v124
	v_mul_f32_e32 v171, v122, v122
	v_max_f32_e32 v122, 0, v127
	v_mul_f32_e32 v127, v123, v123
	v_max_f32_e32 v123, 0, v128
	v_mul_f32_e32 v128, v124, v124
	v_max_f32_e32 v124, 0, v129
	v_ashrrev_i32_e32 v147, 31, v146
	v_lshlrev_b64 v[172:173], 13, v[172:173]
	v_max_f32_e32 v126, 0, v126
	v_mul_f32_e32 v122, v122, v122
	v_mul_f32_e32 v123, v123, v123
	v_max_f32_e32 v125, 0, v125
	v_mul_f32_e32 v124, v124, v124
	v_pk_mul_f32 v[116:117], v[116:117], v[200:201] op_sel_hi:[1,0]
	v_pk_mul_f32 v[114:115], v[114:115], v[200:201] op_sel_hi:[1,0]
	v_lshl_add_u64 v[172:173], s[22:23], 0, v[172:173]
	v_lshlrev_b64 v[146:147], 1, v[146:147]
	v_mul_f32_e32 v126, v126, v126
	v_mul_f32_e32 v125, v125, v125
	v_cvt_pk_bf16_f32 v122, v126, v122
	v_cvt_pk_bf16_f32 v123, v123, v124
	v_cvt_pk_bf16_f32 v124, v171, v127
	v_pk_mul_f32 v[120:121], v[120:121], v[200:201] op_sel_hi:[1,0]
	v_pk_mul_f32 v[118:119], v[118:119], v[200:201] op_sel_hi:[1,0]
	v_max_f32_e32 v114, 0, v114
	v_max_f32_e32 v115, 0, v115
	v_max_f32_e32 v116, 0, v116
	v_lshl_add_u64 v[172:173], v[172:173], 0, v[146:147]
	v_cvt_pk_bf16_f32 v125, v128, v125
	v_max_f32_e32 v117, 0, v117
	global_store_dwordx4 v[172:173], v[122:125], off sc1
	s_nop 1
	v_mul_f32_e32 v123, v114, v114
	v_max_f32_e32 v114, 0, v119
	v_mul_f32_e32 v124, v115, v115
	v_max_f32_e32 v115, 0, v120
	v_mul_f32_e32 v120, v116, v116
	v_max_f32_e32 v116, 0, v121
	v_max_f32_e32 v118, 0, v118
	v_mul_f32_e32 v114, v114, v114
	v_mul_f32_e32 v115, v115, v115
	v_mul_f32_e32 v116, v116, v116
	v_mul_f32_e32 v117, v117, v117
	v_mul_f32_e32 v122, v118, v118
	v_lshl_add_u64 v[118:119], v[172:173], 0, s[26:27]
	v_cvt_pk_bf16_f32 v114, v122, v114
	v_cvt_pk_bf16_f32 v115, v115, v116
	v_cvt_pk_bf16_f32 v116, v123, v124
	v_cvt_pk_bf16_f32 v117, v120, v117
	s_andn2_b64 vcc, exec, s[4:5]
	global_store_dwordx4 v[118:119], v[114:117], off sc1
	s_nop 1
	v_add_u32_e32 v116, s31, v152
	v_ashrrev_i32_e32 v117, 31, v116
	v_lshlrev_b64 v[116:117], 13, v[116:117]
	v_lshl_add_u64 v[116:117], s[22:23], 0, v[116:117]
	s_waitcnt lgkmcnt(6)
	v_pk_mul_f32 v[108:109], v[108:109], v[202:203] op_sel_hi:[1,0]
	v_pk_mul_f32 v[106:107], v[106:107], v[202:203] op_sel_hi:[1,0]
	v_pk_mul_f32 v[112:113], v[112:113], v[202:203] op_sel_hi:[1,0]
	v_pk_mul_f32 v[110:111], v[110:111], v[202:203] op_sel_hi:[1,0]
	v_max_f32_e32 v106, 0, v106
	v_max_f32_e32 v107, 0, v107
	v_max_f32_e32 v108, 0, v108
	v_mul_f32_e32 v115, v106, v106
	v_max_f32_e32 v106, 0, v111
	v_mul_f32_e32 v111, v107, v107
	v_max_f32_e32 v107, 0, v112
	v_mul_f32_e32 v112, v108, v108
	v_max_f32_e32 v108, 0, v113
	v_max_f32_e32 v110, 0, v110
	v_mul_f32_e32 v106, v106, v106
	v_mul_f32_e32 v107, v107, v107
	v_max_f32_e32 v109, 0, v109
	v_mul_f32_e32 v108, v108, v108
	v_pk_mul_f32 v[100:101], v[100:101], v[202:203] op_sel_hi:[1,0]
	v_pk_mul_f32 v[98:99], v[98:99], v[202:203] op_sel_hi:[1,0]
	v_mul_f32_e32 v110, v110, v110
	v_mul_f32_e32 v109, v109, v109
	v_cvt_pk_bf16_f32 v106, v110, v106
	v_cvt_pk_bf16_f32 v107, v107, v108
	v_cvt_pk_bf16_f32 v108, v115, v111
	v_pk_mul_f32 v[104:105], v[104:105], v[202:203] op_sel_hi:[1,0]
	v_pk_mul_f32 v[102:103], v[102:103], v[202:203] op_sel_hi:[1,0]
	v_max_f32_e32 v98, 0, v98
	v_max_f32_e32 v99, 0, v99
	v_max_f32_e32 v100, 0, v100
	v_lshl_add_u64 v[116:117], v[116:117], 0, v[146:147]
	v_cvt_pk_bf16_f32 v109, v112, v109
	v_max_f32_e32 v101, 0, v101
	global_store_dwordx4 v[116:117], v[106:109], off sc1
	s_nop 1
	v_mul_f32_e32 v107, v98, v98
	v_max_f32_e32 v98, 0, v103
	v_mul_f32_e32 v108, v99, v99
	v_max_f32_e32 v99, 0, v104
	v_mul_f32_e32 v104, v100, v100
	v_max_f32_e32 v100, 0, v105
	v_max_f32_e32 v102, 0, v102
	v_mul_f32_e32 v98, v98, v98
	v_mul_f32_e32 v99, v99, v99
	v_mul_f32_e32 v100, v100, v100
	v_mul_f32_e32 v101, v101, v101
	v_mul_f32_e32 v106, v102, v102
	v_lshl_add_u64 v[102:103], v[116:117], 0, s[26:27]
	v_cvt_pk_bf16_f32 v98, v106, v98
	v_cvt_pk_bf16_f32 v99, v99, v100
	v_cvt_pk_bf16_f32 v100, v107, v108
	v_cvt_pk_bf16_f32 v101, v104, v101
	s_mov_b64 s[4:5], -1
	global_store_dwordx4 v[102:103], v[98:101], off sc1
	s_nop 1
	v_add_u32_e32 v100, s31, v154
	v_ashrrev_i32_e32 v101, 31, v100
	v_lshlrev_b64 v[100:101], 13, v[100:101]
	v_lshl_add_u64 v[100:101], s[22:23], 0, v[100:101]
	s_waitcnt lgkmcnt(5)
	v_pk_mul_f32 v[92:93], v[92:93], v[204:205] op_sel_hi:[1,0]
	v_pk_mul_f32 v[90:91], v[90:91], v[204:205] op_sel_hi:[1,0]
	v_pk_mul_f32 v[96:97], v[96:97], v[204:205] op_sel_hi:[1,0]
	v_pk_mul_f32 v[94:95], v[94:95], v[204:205] op_sel_hi:[1,0]
	v_max_f32_e32 v90, 0, v90
	v_max_f32_e32 v91, 0, v91
	v_max_f32_e32 v92, 0, v92
	v_mul_f32_e32 v99, v90, v90
	v_max_f32_e32 v90, 0, v95
	v_mul_f32_e32 v95, v91, v91
	v_max_f32_e32 v91, 0, v96
	v_mul_f32_e32 v96, v92, v92
	v_max_f32_e32 v92, 0, v97
	v_max_f32_e32 v94, 0, v94
	v_mul_f32_e32 v90, v90, v90
	v_mul_f32_e32 v91, v91, v91
	v_max_f32_e32 v93, 0, v93
	v_mul_f32_e32 v92, v92, v92
	v_pk_mul_f32 v[84:85], v[84:85], v[204:205] op_sel_hi:[1,0]
	v_pk_mul_f32 v[82:83], v[82:83], v[204:205] op_sel_hi:[1,0]
	v_mul_f32_e32 v94, v94, v94
	v_mul_f32_e32 v93, v93, v93
	v_cvt_pk_bf16_f32 v90, v94, v90
	v_cvt_pk_bf16_f32 v91, v91, v92
	v_cvt_pk_bf16_f32 v92, v99, v95
	v_pk_mul_f32 v[88:89], v[88:89], v[204:205] op_sel_hi:[1,0]
	v_pk_mul_f32 v[86:87], v[86:87], v[204:205] op_sel_hi:[1,0]
	v_max_f32_e32 v82, 0, v82
	v_max_f32_e32 v83, 0, v83
	v_max_f32_e32 v84, 0, v84
	v_lshl_add_u64 v[100:101], v[100:101], 0, v[146:147]
	v_cvt_pk_bf16_f32 v93, v96, v93
	v_max_f32_e32 v85, 0, v85
	global_store_dwordx4 v[100:101], v[90:93], off sc1
	s_nop 1
	v_mul_f32_e32 v91, v82, v82
	v_max_f32_e32 v82, 0, v87
	v_mul_f32_e32 v92, v83, v83
	v_max_f32_e32 v83, 0, v88
	v_mul_f32_e32 v88, v84, v84
	v_max_f32_e32 v84, 0, v89
	v_max_f32_e32 v86, 0, v86
	v_mul_f32_e32 v82, v82, v82
	v_mul_f32_e32 v83, v83, v83
	v_mul_f32_e32 v84, v84, v84
	v_mul_f32_e32 v85, v85, v85
	v_mul_f32_e32 v90, v86, v86
	v_lshl_add_u64 v[86:87], v[100:101], 0, s[26:27]
	v_cvt_pk_bf16_f32 v82, v90, v82
	v_cvt_pk_bf16_f32 v83, v83, v84
	v_cvt_pk_bf16_f32 v84, v91, v92
	v_cvt_pk_bf16_f32 v85, v88, v85
	s_nop 0
	global_store_dwordx4 v[86:87], v[82:85], off sc1
	s_nop 1
	v_add_u32_e32 v84, s31, v156
	v_ashrrev_i32_e32 v85, 31, v84
	v_lshlrev_b64 v[84:85], 13, v[84:85]
	v_lshl_add_u64 v[84:85], s[22:23], 0, v[84:85]
	s_waitcnt lgkmcnt(4)
	v_pk_mul_f32 v[76:77], v[76:77], v[206:207] op_sel_hi:[1,0]
	v_pk_mul_f32 v[74:75], v[74:75], v[206:207] op_sel_hi:[1,0]
	v_pk_mul_f32 v[80:81], v[80:81], v[206:207] op_sel_hi:[1,0]
	v_pk_mul_f32 v[78:79], v[78:79], v[206:207] op_sel_hi:[1,0]
	v_max_f32_e32 v74, 0, v74
	v_max_f32_e32 v75, 0, v75
	v_max_f32_e32 v76, 0, v76
	v_mul_f32_e32 v83, v74, v74
	v_max_f32_e32 v74, 0, v79
	v_mul_f32_e32 v79, v75, v75
	v_max_f32_e32 v75, 0, v80
	v_mul_f32_e32 v80, v76, v76
	v_max_f32_e32 v76, 0, v81
	v_max_f32_e32 v78, 0, v78
	v_mul_f32_e32 v74, v74, v74
	v_mul_f32_e32 v75, v75, v75
	v_max_f32_e32 v77, 0, v77
	v_mul_f32_e32 v76, v76, v76
	v_pk_mul_f32 v[68:69], v[68:69], v[206:207] op_sel_hi:[1,0]
	v_pk_mul_f32 v[66:67], v[66:67], v[206:207] op_sel_hi:[1,0]
	v_mul_f32_e32 v78, v78, v78
	v_mul_f32_e32 v77, v77, v77
	v_cvt_pk_bf16_f32 v74, v78, v74
	v_cvt_pk_bf16_f32 v75, v75, v76
	v_cvt_pk_bf16_f32 v76, v83, v79
	v_pk_mul_f32 v[72:73], v[72:73], v[206:207] op_sel_hi:[1,0]
	v_pk_mul_f32 v[70:71], v[70:71], v[206:207] op_sel_hi:[1,0]
	v_max_f32_e32 v66, 0, v66
	v_max_f32_e32 v67, 0, v67
	v_max_f32_e32 v68, 0, v68
	v_lshl_add_u64 v[84:85], v[84:85], 0, v[146:147]
	v_cvt_pk_bf16_f32 v77, v80, v77
	v_max_f32_e32 v69, 0, v69
	global_store_dwordx4 v[84:85], v[74:77], off sc1
	s_nop 1
	v_mul_f32_e32 v75, v66, v66
	v_max_f32_e32 v66, 0, v71
	v_mul_f32_e32 v76, v67, v67
	v_max_f32_e32 v67, 0, v72
	v_mul_f32_e32 v72, v68, v68
	v_max_f32_e32 v68, 0, v73
	v_max_f32_e32 v70, 0, v70
	v_mul_f32_e32 v66, v66, v66
	v_mul_f32_e32 v67, v67, v67
	v_mul_f32_e32 v68, v68, v68
	v_mul_f32_e32 v69, v69, v69
	v_mul_f32_e32 v74, v70, v70
	v_lshl_add_u64 v[70:71], v[84:85], 0, s[26:27]
	v_cvt_pk_bf16_f32 v66, v74, v66
	v_cvt_pk_bf16_f32 v67, v67, v68
	v_cvt_pk_bf16_f32 v68, v75, v76
	v_cvt_pk_bf16_f32 v69, v72, v69
	s_nop 0
	global_store_dwordx4 v[70:71], v[66:69], off sc1
	s_nop 1
	v_add_u32_e32 v68, s31, v158
	v_ashrrev_i32_e32 v69, 31, v68
	v_lshlrev_b64 v[68:69], 13, v[68:69]
	v_lshl_add_u64 v[68:69], s[22:23], 0, v[68:69]
	s_waitcnt lgkmcnt(3)
	v_pk_mul_f32 v[60:61], v[60:61], v[208:209] op_sel_hi:[1,0]
	v_pk_mul_f32 v[58:59], v[58:59], v[208:209] op_sel_hi:[1,0]
	v_pk_mul_f32 v[64:65], v[64:65], v[208:209] op_sel_hi:[1,0]
	v_pk_mul_f32 v[62:63], v[62:63], v[208:209] op_sel_hi:[1,0]
	v_max_f32_e32 v58, 0, v58
	v_max_f32_e32 v59, 0, v59
	v_max_f32_e32 v60, 0, v60
	v_mul_f32_e32 v67, v58, v58
	v_max_f32_e32 v58, 0, v63
	v_mul_f32_e32 v63, v59, v59
	v_max_f32_e32 v59, 0, v64
	v_mul_f32_e32 v64, v60, v60
	v_max_f32_e32 v60, 0, v65
	v_max_f32_e32 v62, 0, v62
	v_mul_f32_e32 v58, v58, v58
	v_mul_f32_e32 v59, v59, v59
	v_max_f32_e32 v61, 0, v61
	v_mul_f32_e32 v60, v60, v60
	v_pk_mul_f32 v[52:53], v[52:53], v[208:209] op_sel_hi:[1,0]
	v_pk_mul_f32 v[50:51], v[50:51], v[208:209] op_sel_hi:[1,0]
	v_mul_f32_e32 v62, v62, v62
	v_mul_f32_e32 v61, v61, v61
	v_cvt_pk_bf16_f32 v58, v62, v58
	v_cvt_pk_bf16_f32 v59, v59, v60
	v_cvt_pk_bf16_f32 v60, v67, v63
	v_pk_mul_f32 v[56:57], v[56:57], v[208:209] op_sel_hi:[1,0]
	v_pk_mul_f32 v[54:55], v[54:55], v[208:209] op_sel_hi:[1,0]
	v_max_f32_e32 v50, 0, v50
	v_max_f32_e32 v51, 0, v51
	v_max_f32_e32 v52, 0, v52
	v_lshl_add_u64 v[68:69], v[68:69], 0, v[146:147]
	v_cvt_pk_bf16_f32 v61, v64, v61
	v_max_f32_e32 v53, 0, v53
	global_store_dwordx4 v[68:69], v[58:61], off sc1
	s_nop 1
	v_mul_f32_e32 v59, v50, v50
	v_max_f32_e32 v50, 0, v55
	v_mul_f32_e32 v60, v51, v51
	v_max_f32_e32 v51, 0, v56
	v_mul_f32_e32 v56, v52, v52
	v_max_f32_e32 v52, 0, v57
	v_max_f32_e32 v54, 0, v54
	v_mul_f32_e32 v50, v50, v50
	v_mul_f32_e32 v51, v51, v51
	v_mul_f32_e32 v52, v52, v52
	v_mul_f32_e32 v53, v53, v53
	v_mul_f32_e32 v58, v54, v54
	v_lshl_add_u64 v[54:55], v[68:69], 0, s[26:27]
	v_cvt_pk_bf16_f32 v50, v58, v50
	v_cvt_pk_bf16_f32 v51, v51, v52
	v_cvt_pk_bf16_f32 v52, v59, v60
	v_cvt_pk_bf16_f32 v53, v56, v53
	s_nop 0
	global_store_dwordx4 v[54:55], v[50:53], off sc1
	s_nop 1
	v_add_u32_e32 v52, s31, v160
	v_ashrrev_i32_e32 v53, 31, v52
	v_lshlrev_b64 v[52:53], 13, v[52:53]
	v_lshl_add_u64 v[52:53], s[22:23], 0, v[52:53]
	s_waitcnt lgkmcnt(2)
	v_pk_mul_f32 v[44:45], v[44:45], v[210:211] op_sel_hi:[1,0]
	v_pk_mul_f32 v[42:43], v[42:43], v[210:211] op_sel_hi:[1,0]
	v_pk_mul_f32 v[48:49], v[48:49], v[210:211] op_sel_hi:[1,0]
	v_pk_mul_f32 v[46:47], v[46:47], v[210:211] op_sel_hi:[1,0]
	v_max_f32_e32 v42, 0, v42
	v_max_f32_e32 v43, 0, v43
	v_max_f32_e32 v44, 0, v44
	v_mul_f32_e32 v51, v42, v42
	v_max_f32_e32 v42, 0, v47
	v_mul_f32_e32 v47, v43, v43
	v_max_f32_e32 v43, 0, v48
	v_mul_f32_e32 v48, v44, v44
	v_max_f32_e32 v44, 0, v49
	v_max_f32_e32 v46, 0, v46
	v_mul_f32_e32 v42, v42, v42
	v_mul_f32_e32 v43, v43, v43
	v_max_f32_e32 v45, 0, v45
	v_mul_f32_e32 v44, v44, v44
	v_pk_mul_f32 v[36:37], v[36:37], v[210:211] op_sel_hi:[1,0]
	v_pk_mul_f32 v[34:35], v[34:35], v[210:211] op_sel_hi:[1,0]
	v_mul_f32_e32 v46, v46, v46
	v_mul_f32_e32 v45, v45, v45
	v_cvt_pk_bf16_f32 v42, v46, v42
	v_cvt_pk_bf16_f32 v43, v43, v44
	v_cvt_pk_bf16_f32 v44, v51, v47
	v_pk_mul_f32 v[40:41], v[40:41], v[210:211] op_sel_hi:[1,0]
	v_pk_mul_f32 v[38:39], v[38:39], v[210:211] op_sel_hi:[1,0]
	v_max_f32_e32 v34, 0, v34
	v_max_f32_e32 v35, 0, v35
	v_max_f32_e32 v36, 0, v36
	v_lshl_add_u64 v[52:53], v[52:53], 0, v[146:147]
	v_cvt_pk_bf16_f32 v45, v48, v45
	v_max_f32_e32 v37, 0, v37
	global_store_dwordx4 v[52:53], v[42:45], off sc1
	s_nop 1
	v_mul_f32_e32 v43, v34, v34
	v_max_f32_e32 v34, 0, v39
	v_mul_f32_e32 v44, v35, v35
	v_max_f32_e32 v35, 0, v40
	v_mul_f32_e32 v40, v36, v36
	v_max_f32_e32 v36, 0, v41
	v_max_f32_e32 v38, 0, v38
	v_mul_f32_e32 v34, v34, v34
	v_mul_f32_e32 v35, v35, v35
	v_mul_f32_e32 v36, v36, v36
	v_mul_f32_e32 v37, v37, v37
	v_mul_f32_e32 v42, v38, v38
	v_lshl_add_u64 v[38:39], v[52:53], 0, s[26:27]
	v_cvt_pk_bf16_f32 v34, v42, v34
	v_cvt_pk_bf16_f32 v35, v35, v36
	v_cvt_pk_bf16_f32 v36, v43, v44
	v_cvt_pk_bf16_f32 v37, v40, v37
	s_nop 0
	global_store_dwordx4 v[38:39], v[34:37], off sc1
	s_nop 1
	v_add_u32_e32 v36, s31, v162
	v_ashrrev_i32_e32 v37, 31, v36
	v_lshlrev_b64 v[36:37], 13, v[36:37]
	v_lshl_add_u64 v[36:37], s[22:23], 0, v[36:37]
	s_waitcnt lgkmcnt(1)
	v_pk_mul_f32 v[28:29], v[28:29], v[212:213] op_sel_hi:[1,0]
	v_pk_mul_f32 v[26:27], v[26:27], v[212:213] op_sel_hi:[1,0]
	v_pk_mul_f32 v[32:33], v[32:33], v[212:213] op_sel_hi:[1,0]
	v_pk_mul_f32 v[30:31], v[30:31], v[212:213] op_sel_hi:[1,0]
	v_max_f32_e32 v26, 0, v26
	v_max_f32_e32 v27, 0, v27
	v_max_f32_e32 v28, 0, v28
	v_mul_f32_e32 v35, v26, v26
	v_max_f32_e32 v26, 0, v31
	v_mul_f32_e32 v31, v27, v27
	v_max_f32_e32 v27, 0, v32
	v_mul_f32_e32 v32, v28, v28
	v_max_f32_e32 v28, 0, v33
	v_max_f32_e32 v30, 0, v30
	v_mul_f32_e32 v26, v26, v26
	v_mul_f32_e32 v27, v27, v27
	v_max_f32_e32 v29, 0, v29
	v_mul_f32_e32 v28, v28, v28
	v_pk_mul_f32 v[20:21], v[20:21], v[212:213] op_sel_hi:[1,0]
	v_pk_mul_f32 v[18:19], v[18:19], v[212:213] op_sel_hi:[1,0]
	v_mul_f32_e32 v30, v30, v30
	v_mul_f32_e32 v29, v29, v29
	v_cvt_pk_bf16_f32 v26, v30, v26
	v_cvt_pk_bf16_f32 v27, v27, v28
	v_cvt_pk_bf16_f32 v28, v35, v31
	v_pk_mul_f32 v[24:25], v[24:25], v[212:213] op_sel_hi:[1,0]
	v_pk_mul_f32 v[22:23], v[22:23], v[212:213] op_sel_hi:[1,0]
	v_max_f32_e32 v18, 0, v18
	v_max_f32_e32 v19, 0, v19
	v_max_f32_e32 v20, 0, v20
	v_lshl_add_u64 v[36:37], v[36:37], 0, v[146:147]
	v_cvt_pk_bf16_f32 v29, v32, v29
	v_max_f32_e32 v21, 0, v21
	global_store_dwordx4 v[36:37], v[26:29], off sc1
	s_nop 1
	v_mul_f32_e32 v27, v18, v18
	v_max_f32_e32 v18, 0, v23
	v_mul_f32_e32 v28, v19, v19
	v_max_f32_e32 v19, 0, v24
	v_mul_f32_e32 v24, v20, v20
	v_max_f32_e32 v20, 0, v25
	v_max_f32_e32 v22, 0, v22
	v_mul_f32_e32 v18, v18, v18
	v_mul_f32_e32 v19, v19, v19
	v_mul_f32_e32 v20, v20, v20
	v_mul_f32_e32 v21, v21, v21
	v_mul_f32_e32 v26, v22, v22
	v_lshl_add_u64 v[22:23], v[36:37], 0, s[26:27]
	v_cvt_pk_bf16_f32 v18, v26, v18
	v_cvt_pk_bf16_f32 v19, v19, v20
	v_cvt_pk_bf16_f32 v20, v27, v28
	v_cvt_pk_bf16_f32 v21, v24, v21
	s_nop 0
	global_store_dwordx4 v[22:23], v[18:21], off sc1
	s_nop 1
	v_add_u32_e32 v20, s31, v164
	v_ashrrev_i32_e32 v21, 31, v20
	v_lshlrev_b64 v[20:21], 13, v[20:21]
	v_lshl_add_u64 v[20:21], s[22:23], 0, v[20:21]
	s_waitcnt lgkmcnt(0)
	v_pk_mul_f32 v[12:13], v[12:13], v[214:215] op_sel_hi:[1,0]
	v_pk_mul_f32 v[10:11], v[10:11], v[214:215] op_sel_hi:[1,0]
	v_pk_mul_f32 v[16:17], v[16:17], v[214:215] op_sel_hi:[1,0]
	v_pk_mul_f32 v[14:15], v[14:15], v[214:215] op_sel_hi:[1,0]
	v_max_f32_e32 v10, 0, v10
	v_max_f32_e32 v11, 0, v11
	v_max_f32_e32 v12, 0, v12
	v_mul_f32_e32 v19, v10, v10
	v_max_f32_e32 v10, 0, v15
	v_mul_f32_e32 v15, v11, v11
	v_max_f32_e32 v11, 0, v16
	v_mul_f32_e32 v16, v12, v12
	v_max_f32_e32 v12, 0, v17
	v_max_f32_e32 v14, 0, v14
	v_mul_f32_e32 v10, v10, v10
	v_mul_f32_e32 v11, v11, v11
	v_max_f32_e32 v13, 0, v13
	v_mul_f32_e32 v12, v12, v12
	v_pk_mul_f32 v[4:5], v[4:5], v[214:215] op_sel_hi:[1,0]
	v_pk_mul_f32 v[2:3], v[2:3], v[214:215] op_sel_hi:[1,0]
	v_mul_f32_e32 v14, v14, v14
	v_mul_f32_e32 v13, v13, v13
	v_cvt_pk_bf16_f32 v10, v14, v10
	v_cvt_pk_bf16_f32 v11, v11, v12
	v_cvt_pk_bf16_f32 v12, v19, v15
	v_pk_mul_f32 v[8:9], v[8:9], v[214:215] op_sel_hi:[1,0]
	v_pk_mul_f32 v[6:7], v[6:7], v[214:215] op_sel_hi:[1,0]
	v_max_f32_e32 v2, 0, v2
	v_max_f32_e32 v3, 0, v3
	v_max_f32_e32 v4, 0, v4
	v_lshl_add_u64 v[20:21], v[20:21], 0, v[146:147]
	v_cvt_pk_bf16_f32 v13, v16, v13
	v_max_f32_e32 v5, 0, v5
	global_store_dwordx4 v[20:21], v[10:13], off sc1
	s_nop 1
	v_mul_f32_e32 v11, v2, v2
	v_max_f32_e32 v2, 0, v7
	v_mul_f32_e32 v12, v3, v3
	v_max_f32_e32 v3, 0, v8
	v_mul_f32_e32 v8, v4, v4
	v_max_f32_e32 v4, 0, v9
	v_max_f32_e32 v6, 0, v6
	v_mul_f32_e32 v2, v2, v2
	v_mul_f32_e32 v3, v3, v3
	v_mul_f32_e32 v4, v4, v4
	v_mul_f32_e32 v5, v5, v5
	v_mul_f32_e32 v10, v6, v6
	v_lshl_add_u64 v[6:7], v[20:21], 0, s[26:27]
	v_cvt_pk_bf16_f32 v2, v10, v2
	v_cvt_pk_bf16_f32 v3, v3, v4
	v_cvt_pk_bf16_f32 v4, v11, v12
	v_cvt_pk_bf16_f32 v5, v8, v5
	s_nop 0
	global_store_dwordx4 v[6:7], v[2:5], off sc1
	s_nop 1
	s_cbranch_vccnz .LBB0_618
	s_andn2_b64 vcc, exec, s[16:17]
	s_cbranch_vccnz .LBB0_617
	s_barrier
	s_branch .LBB0_617
